# MA router-weight staging: 8 loads in flight instead of load/wait/ds_write per trip (on top of MA DPP version)
# baseline (speedup 1.0000x reference)
; #define GAS __attribute__((address_space(1)))
; #define LAS __attribute__((address_space(3)))
; __device__ __forceinline__ void phase_ma(const Params& p, Frame& F, int l, const bool fd, const float* xin32) {
;     ...
;     for (int s = 4 * F.tid; s < D * NE; s += 4 * NTHR) *(LAS f32x4*)(wrp + s) = *(const GAS f32x4*)(wr + s);
.LBB0_599:
	s_mov_b64 s[6:7], 0x2000
	v_lshl_add_u64 v[4:5], v[0:1], 0, s[6:7]
	global_load_dwordx4 v[32:35], v[0:1], off
	v_lshl_add_u64 v[6:7], v[4:5], 0, s[6:7]
	global_load_dwordx4 v[36:39], v[4:5], off
	v_lshl_add_u64 v[8:9], v[6:7], 0, s[6:7]
	global_load_dwordx4 v[40:43], v[6:7], off
	v_lshl_add_u64 v[10:11], v[8:9], 0, s[6:7]
	global_load_dwordx4 v[44:47], v[8:9], off
	v_lshl_add_u64 v[12:13], v[10:11], 0, s[6:7]
	global_load_dwordx4 v[48:51], v[10:11], off
	v_lshl_add_u64 v[14:15], v[12:13], 0, s[6:7]
	global_load_dwordx4 v[52:55], v[12:13], off
	v_lshl_add_u64 v[16:17], v[14:15], 0, s[6:7]
	global_load_dwordx4 v[56:59], v[14:15], off
	global_load_dwordx4 v[60:63], v[16:17], off
	s_waitcnt vmcnt(7)
	ds_write_b128 v3, v[32:35]
	s_waitcnt vmcnt(6)
	ds_write_b128 v3, v[36:39] offset:8192
	s_waitcnt vmcnt(5)
	ds_write_b128 v3, v[40:43] offset:16384
	s_waitcnt vmcnt(4)
	ds_write_b128 v3, v[44:47] offset:24576
	s_waitcnt vmcnt(3)
	ds_write_b128 v3, v[48:51] offset:32768
	s_waitcnt vmcnt(2)
	ds_write_b128 v3, v[52:55] offset:40960
	s_waitcnt vmcnt(1)
	ds_write_b128 v3, v[56:59] offset:49152
	s_waitcnt vmcnt(0)
	ds_write_b128 v3, v[60:63] offset:57344
	s_or_b64 exec, exec, s[2:3]
